# v25: waves 1-7 prefetch next Resid-phase weight K-tiles 0/1 into LDS during the grid barrier; Resid prologue skips its B DMAs
# speedup vs baseline: 1.0015x; 1.0015x over previous
.LBB0_1020:
	s_mov_b32 s32, 0
	s_add_i32 s57, 0, 0x23fc0
	s_add_i32 s58, 0, 0x23fc4
	v_mbcnt_lo_u32_b32 v0, -1, 0
	v_writelane_b32 v254, s57, 62
	s_movk_i32 s68, 0x7f
	s_mov_b32 s74, 0x7fffffe0
	v_mov_b32_e32 v1, 0
	s_mov_b64 s[42:43], 0x80
	v_mov_b64_e32 v[130:131], 0x100
	v_mov_b64_e32 v[132:133], 0xff
	s_movk_i32 s45, 0x90
	s_mov_b32 s75, 0xd700000
	v_mov_b32_e32 v184, 0x358637bd
	s_mov_b32 s80, 0x800000
	s_movk_i32 s84, 0x1400
	v_mov_b32_e32 v185, 0x3727c5ac
	s_movk_i32 s85, 0x800
	s_movk_i32 s82, 0x84
	s_add_i32 s83, 0, 0x19400
	s_mov_b32 s1, 1
	s_add_i32 s52, 0, 0x1b500
	s_mov_b32 s53, 0xf149f2ca
	s_mov_b32 s76, 0xefa18f08
	s_add_i32 s77, 0, 0x11000
	s_mov_b32 s86, 0x3e38aa3b
	s_movk_i32 s81, 0xf00
	s_mov_b32 s87, 0x12f00000
	s_movk_i32 s88, 0xc00
	s_mov_b64 s[90:91], 0x800
	s_movk_i32 s94, 0x51
	s_movk_i32 s95, 0xb1
	s_movk_i32 s56, 0x1600
	v_mov_b32_e32 v186, 0x1000
	v_mov_b32_e32 v187, 0x2000
	v_mov_b32_e32 v188, 1
	v_mbcnt_hi_u32_b32 v189, -1, v0
	v_mov_b32_e32 v190, 0xf149f2ca
	v_mov_b32_e32 v191, 0x7f800000
	v_mov_b32_e32 v192, 0xe00
	v_mov_b32_e32 v193, 0x12b00000
	v_mov_b32_e32 v194, 0x12700000
	v_mov_b64_e32 v[134:135], 0x280
	v_mov_b64_e32 v[136:137], 0x27f
	v_mov_b64_e32 v[138:139], 0x580
	v_mov_b64_e32 v[140:141], 0x57f
	s_mov_b32 s59, 0
	v_writelane_b32 v254, s58, 63
	s_branch .LBB0_1022

.LBB0_1592:
	s_and_b64 vcc, exec, s[2:3]
	s_cbranch_vccnz .LBB0_1634
	v_bfe_i32 v3, v14, 27, 1
	v_lshlrev_b32_e32 v2, 4, v14
	v_lshrrev_b32_e32 v3, 22, v3
	v_add_u32_e32 v3, v2, v3
	v_and_b32_e32 v3, 0xfffffc00, v3
	v_ashrrev_i32_e32 v0, 31, v14
	v_sub_u32_e32 v3, v2, v3
	v_lshrrev_b32_e32 v0, 26, v0
	v_lshrrev_b32_e32 v4, 4, v3
	v_add_u32_e32 v0, v14, v0
	v_bitop3_b32 v4, v4, v3, 32 bitop3:0x6c
	v_ashrrev_i32_e32 v3, 31, v3
	v_readlane_b32 s0, v254, 5
	v_ashrrev_i32_e32 v0, 6, v0
	v_lshrrev_b32_e32 v3, 26, v3
	s_add_u32 s2, s0, 0xb00000
	v_readlane_b32 s0, v254, 13
	v_lshlrev_b32_e32 v5, 3, v0
	v_add_u32_e32 v3, v4, v3
	s_addc_u32 s3, s0, 0
	v_readlane_b32 s0, v254, 43
	v_and_b32_e32 v5, -16, v5
	v_ashrrev_i32_e32 v3, 6, v3
	v_lshlrev_b32_e32 v0, 5, v0
	v_readlane_b32 s1, v254, 44
	s_add_u32 s0, s64, s0
	v_readlane_b32 s5, v255, 11
	v_add_u32_e32 v5, v3, v5
	v_and_b32_e32 v15, 32, v0
	v_mul_i32_i24_e32 v0, 64, v3
	s_addc_u32 s1, s65, s1
	s_lshl_b32 s5, s5, 1
	v_sub_u32_e32 v0, v4, v0
	v_lshlrev_b32_e32 v4, 1, v5
	v_lshrrev_b32_e32 v6, 2, v5
	v_and_b32_e32 v3, 3, v3
	s_add_u32 s5, s0, s5
	v_readlane_b32 s12, v254, 29
	v_ashrrev_i16_sdwa v0, v188, sext(v0) dst_sel:DWORD dst_unused:UNUSED_PAD src0_sel:DWORD src1_sel:BYTE_0
	v_and_b32_e32 v4, 24, v4
	v_and_b32_e32 v6, 4, v6
	v_and_or_b32 v3, v5, s74, v3
	s_addc_u32 s7, s1, 0
	v_readlane_b32 s13, v254, 30
	v_bfe_i32 v16, v0, 0, 16
	v_or3_b32 v3, v3, v6, v4
	s_and_b64 s[0:1], s[12:13], exec
	v_add_u32_e32 v0, v15, v16
	v_mul_lo_u32 v17, v5, s4
	v_mul_lo_u32 v3, v3, s4
	v_add_u32_e32 v2, 0x2000, v2
	s_cselect_b32 s22, s3, s7
	s_cselect_b32 s23, s2, s5
	s_ashr_i32 s2, s6, 6
	v_add_lshl_u32 v142, v0, v17, 1
	v_add_lshl_u32 v0, v3, v0, 1
	v_ashrrev_i32_e32 v3, 31, v2
	s_ashr_i32 s5, s4, 31
	v_lshrrev_b32_e32 v3, 22, v3
	s_ashr_i32 s3, s6, 8
	s_lshl_b64 s[8:9], s[4:5], 8
	s_lshl_b64 s[10:11], s[4:5], 9
	s_lshl_b32 s24, s2, 10
	v_add_u32_e32 v3, v2, v3
	s_and_b64 s[0:1], s[12:13], exec
	v_ashrrev_i32_e32 v3, 10, v3
	v_readlane_b32 s0, v254, 7
	v_mul_i32_i24_e32 v4, 0x400, v3
	v_readlane_b32 s1, v254, 8
	v_sub_u32_e32 v2, v2, v4
	s_cselect_b32 s25, s51, s1
	s_cselect_b32 s26, s50, s0
	s_ashr_i32 s0, s41, 31
	v_lshrrev_b32_e32 v4, 4, v2
	s_mul_i32 s0, s10, s0
	s_mul_hi_u32 s1, s10, s41
	v_bitop3_b32 v2, v4, v2, 32 bitop3:0x6c
	s_add_i32 s7, s1, s0
	s_lshr_b64 s[0:1], s[4:5], 23
	v_ashrrev_i32_e32 v5, 31, v2
	s_mul_i32 s1, s0, s41
	v_lshrrev_b32_e32 v5, 26, v5
	s_add_i32 s7, s7, s1
	s_ashr_i32 s1, s33, 31
	v_lshlrev_b32_e32 v4, 3, v3
	v_add_u32_e32 v5, v2, v5
	s_mul_i32 s1, s10, s1
	s_mul_hi_u32 s13, s10, s33
	v_and_b32_e32 v4, -16, v4
	v_ashrrev_i32_e32 v6, 6, v5
	v_lshlrev_b32_e32 v3, 5, v3
	s_add_i32 s1, s13, s1
	s_mul_i32 s0, s0, s33
	v_add_u32_e32 v4, v6, v4
	v_and_b32_e32 v18, 32, v3
	v_and_b32_e32 v3, 0xc0, v5
	s_add_i32 s1, s1, s0
	s_mul_i32 s0, s10, s33
	v_sub_u32_e32 v2, v2, v3
	v_lshlrev_b32_e32 v3, 1, v4
	v_lshrrev_b32_e32 v5, 2, v4
	v_and_b32_e32 v6, 3, v6
	s_add_u32 s20, s23, s0
	v_ashrrev_i16_sdwa v2, v188, sext(v2) dst_sel:DWORD dst_unused:UNUSED_PAD src0_sel:DWORD src1_sel:BYTE_0
	v_and_b32_e32 v3, 24, v3
	v_and_b32_e32 v5, 4, v5
	v_and_or_b32 v6, v4, s74, v6
	s_addc_u32 s21, s22, s1
	s_add_i32 s27, s24, 0
	v_bfe_i32 v19, v2, 0, 16
	v_or3_b32 v3, v6, v5, v3
	s_cmp_eq_u32 s32, 1
	s_cbranch_scc1 .Lrp_pf
	s_add_i32 m0, s27, 0x10000
	v_add_u32_e32 v2, v18, v19
	v_mul_lo_u32 v3, v3, s4
	global_load_lds_dwordx4 v0, s[20:21]
	s_add_i32 m0, s27, 0x12000
	v_add_lshl_u32 v146, v3, v2, 1
	s_add_u32 s0, s20, s8
	global_load_lds_dwordx4 v146, s[20:21]
	s_addc_u32 s1, s21, s9
	s_add_i32 m0, s27, 0x14000
	s_mul_i32 s12, s10, s41
	v_mov_b32_e32 v147, v1
	global_load_lds_dwordx4 v0, s[0:1]
	s_add_i32 m0, s27, 0x16000
	v_lshl_add_u64 v[6:7], s[0:1], 0, v[0:1]
	v_lshl_add_u64 v[8:9], s[0:1], 0, v[146:147]
	global_load_lds_dwordx4 v146, s[0:1]
	s_add_u32 s0, s26, s12
	s_addc_u32 s1, s25, s7
	s_add_i32 s28, s27, 0x2000
	v_mul_lo_u32 v20, v4, s4
	s_mov_b32 m0, s27
	s_add_u32 s12, s0, s8
	v_add_lshl_u32 v144, v2, v20, 1
	global_load_lds_dwordx4 v142, s[0:1]
	s_mov_b32 m0, s28
	s_addc_u32 s13, s1, s9
	s_add_i32 s29, s27, 0x4000
	global_load_lds_dwordx4 v144, s[0:1]
	s_mov_b32 m0, s29
	s_add_i32 s30, s27, 0x6000
	global_load_lds_dwordx4 v142, s[12:13]
	s_mov_b32 m0, s30
	v_mov_b32_e32 v143, v1
	global_load_lds_dwordx4 v144, s[12:13]
	v_mov_b32_e32 v145, v1
	v_lshl_add_u64 v[2:3], s[20:21], 0, v[0:1]
	v_lshl_add_u64 v[4:5], s[20:21], 0, v[146:147]
	v_lshl_add_u64 v[10:11], s[0:1], 0, v[142:143]
	v_lshl_add_u64 v[12:13], s[0:1], 0, v[144:145]
	s_add_i32 m0, s27, 0x18000
	v_lshl_add_u64 v[2:3], v[2:3], 0, s[42:43]
	s_add_i32 s31, s27, 0x8000
	global_load_lds_dwordx4 v[2:3], off
	v_lshl_add_u64 v[2:3], v[4:5], 0, s[42:43]
	s_add_i32 m0, s27, 0x1a000
	s_add_i32 s34, s27, 0xa000
	global_load_lds_dwordx4 v[2:3], off
	v_lshl_add_u64 v[2:3], v[10:11], 0, s[42:43]
	s_mov_b32 m0, s31
	s_nop 0
	global_load_lds_dwordx4 v[2:3], off
	v_lshl_add_u64 v[2:3], v[12:13], 0, s[42:43]
	s_mov_b32 m0, s34
	s_nop 0
	global_load_lds_dwordx4 v[2:3], off
	s_add_i32 m0, s27, 0x1c000
	v_lshl_add_u64 v[2:3], v[6:7], 0, s[42:43]
	global_load_lds_dwordx4 v[2:3], off
	v_lshl_add_u64 v[2:3], v[8:9], 0, s[42:43]
	s_add_i32 m0, s27, 0x1e000
	s_nop 0
	global_load_lds_dwordx4 v[2:3], off
	s_branch .Lrp_join
.Lrp_pf:
	s_add_i32 m0, s27, 0x10000
	v_add_u32_e32 v2, v18, v19
	v_mul_lo_u32 v3, v3, s4
	s_add_i32 m0, s27, 0x12000
	v_add_lshl_u32 v146, v3, v2, 1
	s_add_u32 s0, s20, s8
	s_addc_u32 s1, s21, s9
	s_add_i32 m0, s27, 0x14000
	s_mul_i32 s12, s10, s41
	v_mov_b32_e32 v147, v1
	s_add_i32 m0, s27, 0x16000
	v_lshl_add_u64 v[6:7], s[0:1], 0, v[0:1]
	v_lshl_add_u64 v[8:9], s[0:1], 0, v[146:147]
	s_add_u32 s0, s26, s12
	s_addc_u32 s1, s25, s7
	s_add_i32 s28, s27, 0x2000
	v_mul_lo_u32 v20, v4, s4
	s_mov_b32 m0, s27
	s_add_u32 s12, s0, s8
	v_add_lshl_u32 v144, v2, v20, 1
	global_load_lds_dwordx4 v142, s[0:1]
	s_mov_b32 m0, s28
	s_addc_u32 s13, s1, s9
	s_add_i32 s29, s27, 0x4000
	global_load_lds_dwordx4 v144, s[0:1]
	s_mov_b32 m0, s29
	s_add_i32 s30, s27, 0x6000
	global_load_lds_dwordx4 v142, s[12:13]
	s_mov_b32 m0, s30
	v_mov_b32_e32 v143, v1
	global_load_lds_dwordx4 v144, s[12:13]
	v_mov_b32_e32 v145, v1
	v_lshl_add_u64 v[2:3], s[20:21], 0, v[0:1]
	v_lshl_add_u64 v[4:5], s[20:21], 0, v[146:147]
	v_lshl_add_u64 v[10:11], s[0:1], 0, v[142:143]
	v_lshl_add_u64 v[12:13], s[0:1], 0, v[144:145]
	s_add_i32 m0, s27, 0x18000
	v_lshl_add_u64 v[2:3], v[2:3], 0, s[42:43]
	s_add_i32 s31, s27, 0x8000
	v_lshl_add_u64 v[2:3], v[4:5], 0, s[42:43]
	s_add_i32 m0, s27, 0x1a000
	s_add_i32 s34, s27, 0xa000
	v_lshl_add_u64 v[2:3], v[10:11], 0, s[42:43]
	s_mov_b32 m0, s31
	s_nop 0
	global_load_lds_dwordx4 v[2:3], off
	v_lshl_add_u64 v[2:3], v[12:13], 0, s[42:43]
	s_mov_b32 m0, s34
	s_nop 0
	global_load_lds_dwordx4 v[2:3], off
	s_add_i32 m0, s27, 0x1c000
	v_lshl_add_u64 v[2:3], v[6:7], 0, s[42:43]
	v_lshl_add_u64 v[2:3], v[8:9], 0, s[42:43]
	s_add_i32 m0, s27, 0x1e000
	s_nop 0
.Lrp_join:
	s_cmp_eq_u32 s3, 1
	s_cselect_b64 s[12:13], -1, 0
	s_cmp_lg_u32 s3, 1
	s_cbranch_scc1 .LBB0_1595
	s_barrier
.LBB0_1595:
	s_cmp_eq_u32 s32, 1
	s_cbranch_scc1 .Lrp_w1
	s_waitcnt vmcnt(8)
	s_branch .Lrp_w1d
.Lrp_w1:
	s_waitcnt vmcnt(4)
.Lrp_w1d:
	s_barrier
	s_and_b32 s35, s2, 3
	s_lshr_b32 s2, s5, 26
	v_bfe_u32 v2, v14, 4, 2
	v_and_b32_e32 v3, 15, v14
	v_lshlrev_b32_e32 v5, 4, v2
	s_add_i32 s2, s4, s2
	v_lshl_or_b32 v160, s3, 6, v3
	v_lshl_or_b32 v3, v3, 6, v5
	v_lshlrev_b32_e32 v5, 2, v14
	s_ashr_i32 s36, s2, 6
	s_lshl_b32 s2, s3, 13
	v_and_b32_e32 v5, 32, v5
	v_bitop3_b32 v6, v3, s2, v5 bitop3:0xde
	s_lshl_b32 s2, s35, 12
	v_readlane_b32 s14, v254, 29
	v_lshlrev_b32_e32 v4, 3, v2
	v_bitop3_b32 v161, v3, s2, v5 bitop3:0xde
	v_cmp_eq_u32_e64 s[2:3], 0, v2
	v_add_u32_e32 v2, v17, v15
	v_readlane_b32 s15, v254, 30
	s_cmp_gt_i32 s4, 63
	v_add_lshl_u32 v2, v2, v16, 1
	v_mov_b32_e32 v3, v1
	v_cndmask_b32_e64 v148, 1.0, 0.5, s[14:15]
	s_cselect_b64 s[14:15], -1, 0
	s_add_i32 s37, s36, -2
	v_lshl_add_u64 v[150:151], s[8:9], 0, v[2:3]
	v_add_u32_e32 v2, v20, v18
	s_cmpk_lt_u32 s6, 0x100
	v_add_lshl_u32 v2, v2, v19, 1
	v_lshl_or_b32 v162, s35, 5, v4
	s_cselect_b64 s[16:17], -1, 0
	s_mov_b32 s38, 0
	v_mov_b32_e32 v149, v148
	v_lshl_add_u64 v[152:153], s[8:9], 0, v[2:3]
	v_add_u32_e32 v163, 0, v6
	s_cmp_eq_u32 s32, 1
	s_cbranch_scc1 .Lrp_w2
	s_waitcnt vmcnt(6)
	s_branch .Lrp_w2d
.Lrp_w2:
	s_waitcnt vmcnt(2)
.Lrp_w2d:
	s_mov_b32 s32, 0
	s_barrier
	s_branch .LBB0_1598

.LBB0_1657:
	v_readlane_b32 s50, v254, 38
	s_add_i32 s50, s50, 1
	s_waitcnt lgkmcnt(0)
	s_cmp_ge_i32 s50, s63
	s_cbranch_scc1 .LBB0_1669
	s_waitcnt vmcnt(0)
	v_mov_b32_e32 v0, v173
	s_waitcnt vmcnt(0)
	s_barrier
	s_nop 0
	s_mov_b32 s32, 0
	s_cmp_eq_u32 s69, 0x100
	s_cbranch_scc0 .Lpf_cfg_done
	s_add_i32 s2, s50, -1
	s_cmp_lt_u32 s2, 32
	s_cbranch_scc0 .Lpf_cfg_done
	s_and_b32 s3, s2, 7
	s_lshr_b32 s4, s2, 3
	s_cmp_eq_u32 s3, 5
	s_cbranch_scc1 .Lpf_cfg_out
	s_cmp_eq_u32 s3, 1
	s_cbranch_scc1 .Lpf_cfg_down
	s_cmp_eq_u32 s3, 7
	s_cbranch_scc0 .Lpf_cfg_done
.Lpf_cfg_down:
	s_lshr_b32 s5, s3, 2
	s_lshl_b32 s6, s4, 1
	s_add_i32 s6, s6, s5
	s_mul_i32 s6, s6, 0x1080000
	s_add_i32 s6, s6, 0xb00000
	s_movk_i32 s5, 0xb00
	s_branch .Lpf_cfg_set
.Lpf_cfg_out:
	s_lshr_b32 s6, s4, 1
	s_lshl_b32 s6, s6, 21
	s_and_b32 s7, s4, 1
	s_lshl_b32 s7, s7, 23
	s_add_i32 s6, s6, s7
	s_add_i32 s6, s6, 0x8e00000
	s_movk_i32 s5, 0x400
.Lpf_cfg_set:
	v_readlane_b32 s7, v254, 0
	s_nop 0
	s_lshr_b32 s7, s7, 6
	s_mul_i32 s7, s7, s5
	s_lshl_b32 s7, s7, 9
	s_add_u32 s6, s6, s7
	s_add_u32 s6, s64, s6
	s_addc_u32 s7, s65, 0
	s_mov_b32 s32, 1
.Lpf_cfg_done:
	v_cmp_eq_u32_e32 vcc, 0, v0
	s_and_saveexec_b64 s[0:1], vcc
	v_readlane_b32 s47, v254, 37
	s_cbranch_execz .Lpf_entry
	v_mov_b32_e32 v0, s57
	s_getreg_b32 s2, hwreg(HW_REG_XCC_ID, 0, 4)
	s_waitcnt vmcnt(0) expcnt(0) lgkmcnt(0)
	ds_read_b32 v3, v0
	v_mov_b32_e32 v0, s58
	ds_read_b32 v0, v0
	s_and_b32 s33, s2, 15
	s_waitcnt lgkmcnt(1)
	v_cmp_ne_u32_e32 vcc, 0, v3
	s_cbranch_vccnz .LBB0_1675
	s_add_u32 s2, s64, 0xd680200
	s_addc_u32 s3, s65, 0
	s_add_u32 s4, s64, 0xd680400
	s_addc_u32 s5, s65, 0
	s_add_u32 s6, s64, 0xd680500
	s_addc_u32 s7, s65, 0
	s_add_u32 s8, s64, 0xd680600
	s_addc_u32 s9, s65, 0
	s_add_u32 s10, s64, 0xd680700
	s_addc_u32 s11, s65, 0
	s_add_u32 s12, s64, 0xd680800
	s_addc_u32 s13, s65, 0
	s_add_u32 s14, s64, 0xd680900
	s_addc_u32 s15, s65, 0
	s_add_u32 s16, s64, 0xd680a00
	s_addc_u32 s17, s65, 0
	s_add_u32 s18, s64, 0xd680b00
	s_addc_u32 s19, s65, 0
	s_add_u32 s20, s64, 0xd680c00
	s_addc_u32 s21, s65, 0
	s_add_u32 s22, s64, 0xd680d00
	s_addc_u32 s23, s65, 0
	s_add_u32 s24, s64, 0xd680e00
	s_addc_u32 s25, s65, 0
	s_add_u32 s26, s64, 0xd680f00
	s_addc_u32 s27, s65, 0
	s_add_u32 s28, s64, 0xd681000
	s_addc_u32 s29, s65, 0
	s_add_u32 s30, s64, 0xd681100
	s_addc_u32 s31, s65, 0
	s_add_u32 s34, s64, 0xd681200
	s_addc_u32 s35, s65, 0
	s_add_u32 s36, s64, 0xd681300
	s_mov_b32 s44, s69
	s_addc_u32 s37, s65, 0
	s_mov_b32 s46, 1
	s_branch .LBB0_1662

.Lpf_entry:
	s_or_b64 exec, exec, s[0:1]
	s_cmp_eq_u32 s32, 1
	s_cbranch_scc0 .LBB0_1711
	s_mov_b32 s10, m0
	v_and_b32_e32 v2, 63, v173
	v_lshrrev_b32_e32 v3, 6, v173
	v_lshrrev_b32_e32 v4, 2, v3
	v_lshlrev_b32_e32 v4, 5, v4
	v_lshrrev_b32_e32 v5, 4, v2
	v_lshl_add_u32 v4, v5, 3, v4
	v_bfe_u32 v5, v3, 1, 1
	v_lshl_add_u32 v4, v5, 2, v4
	v_bfe_u32 v5, v2, 2, 2
	v_add_u32_e32 v4, v4, v5
	v_and_b32_e32 v5, 3, v2
	v_lshlrev_b32_e32 v5, 3, v5
	v_lshrrev_b32_e32 v6, 5, v2
	v_lshlrev_b32_e32 v6, 4, v6
	v_xor_b32_e32 v5, v5, v6
	v_and_b32_e32 v6, 1, v3
	v_lshl_add_u32 v5, v6, 5, v5
	v_mul_lo_u32 v4, v4, s5
	s_nop 1
	v_readfirstlane_b32 s9, v3
	v_add_lshl_u32 v4, v4, v5, 1
	s_lshl_b32 s8, s5, 7
	s_lshl_b32 s12, s5, 8
	v_add_u32_e32 v5, s8, v4
	s_lshl_b32 s11, s9, 10
	s_add_u32 s12, s6, s12
	s_addc_u32 s13, s7, 0
	s_add_u32 s14, s6, 0x80
	s_addc_u32 s15, s7, 0
	s_add_u32 s16, s12, 0x80
	s_addc_u32 s17, s13, 0
	s_add_i32 m0, s11, 0x10000
	s_nop 0
	global_load_lds_dwordx4 v4, s[6:7]
	s_add_i32 m0, s11, 0x12000
	s_nop 0
	global_load_lds_dwordx4 v5, s[6:7]
	s_add_i32 m0, s11, 0x14000
	s_nop 0
	global_load_lds_dwordx4 v4, s[12:13]
	s_add_i32 m0, s11, 0x16000
	s_nop 0
	global_load_lds_dwordx4 v5, s[12:13]
	s_add_i32 m0, s11, 0x18000
	s_nop 0
	global_load_lds_dwordx4 v4, s[14:15]
	s_add_i32 m0, s11, 0x1a000
	s_nop 0
	global_load_lds_dwordx4 v5, s[14:15]
	s_add_i32 m0, s11, 0x1c000
	s_nop 0
	global_load_lds_dwordx4 v4, s[16:17]
	s_add_i32 m0, s11, 0x1e000
	s_nop 0
	global_load_lds_dwordx4 v5, s[16:17]
	s_cmp_eq_u32 s9, 1
	s_cbranch_scc0 .Lpf_exit
	v_subrev_u32_e32 v4, 64, v4
	v_subrev_u32_e32 v5, 64, v5
	s_mov_b32 m0, 0x10000
	s_nop 0
	global_load_lds_dwordx4 v4, s[6:7]
	s_mov_b32 m0, 0x12000
	s_nop 0
	global_load_lds_dwordx4 v5, s[6:7]
	s_mov_b32 m0, 0x14000
	s_nop 0
	global_load_lds_dwordx4 v4, s[12:13]
	s_mov_b32 m0, 0x16000
	s_nop 0
	global_load_lds_dwordx4 v5, s[12:13]
	s_mov_b32 m0, 0x18000
	s_nop 0
	global_load_lds_dwordx4 v4, s[14:15]
	s_mov_b32 m0, 0x1a000
	s_nop 0
	global_load_lds_dwordx4 v5, s[14:15]
	s_mov_b32 m0, 0x1c000
	s_nop 0
	global_load_lds_dwordx4 v4, s[16:17]
	s_mov_b32 m0, 0x1e000
	s_nop 0
	global_load_lds_dwordx4 v5, s[16:17]
.Lpf_exit:
	s_mov_b32 m0, s10
	s_branch .LBB0_1711
